# opt17: opt16 + G5 final EpiMerge epilogue regenerated, gate loads 4 steps ahead (ring), saddr loads/stores
# baseline (speedup 1.0000x reference)
; __device__ __forceinline__ unsigned cvt_pk_bf16(float lo, float hi) { f32x2_t v = {lo, hi}; bf16x2_t b = __builtin_convertvector(v, bf16x2_t); return __builtin_bit_cast(unsigned, b); }
; __device__ __forceinline__ float bf_lo(unsigned w) { return __uint_as_float(w << 16); }
; __device__ __forceinline__ float bf_hi(unsigned w) { return __uint_as_float(w & 0xffff0000u); }
;     __device__ __forceinline__ void operator()(const Acc& acc, const Unit& u, int wr, int wc, int fr, int fq) const {
;         const int row0 = u.pm * BM + wr * 64 + fr, col0 = u.pn * BM + wc * 32 + 8 * fq;
; #pragma unroll
;         for (int ai = 0; ai < 2; ++ai)
; #pragma unroll
;             for (int m = 0; m < 4; ++m) {
;                 const int row = row0 + ai * HALF + m * 16;
; #pragma unroll
;                 for (int bj = 0; bj < 2; ++bj) {
;                     const int col = col0 + bj * HALF;
;                     const u32x4 gb = *(const u32x4*)(P + (size_t)row * PP + C_GB + col);
;                     const float rb[8] = {bf_lo(gb.x), bf_hi(gb.x), bf_lo(gb.y), bf_hi(gb.y), bf_lo(gb.z), bf_hi(gb.z), bf_lo(gb.w), bf_hi(gb.w)};
;                     float o[8];
; #pragma unroll
;                     for (int n = 0; n < 2; ++n)
; #pragma unroll
;                         for (int e = 0; e < 4; ++e) o[4 * n + e] = acc[ai][bj][m][n][e] * rb[4 * n + e];
;                     u32x4 w; w.x = cvt_pk_bf16(o[0], o[1]); w.y = cvt_pk_bf16(o[2], o[3]); w.z = cvt_pk_bf16(o[4], o[5]); w.w = cvt_pk_bf16(o[6], o[7]);
;                     *(u32x4*)(OUT + (size_t)row * DM + col) = w;
;                 }
;             }
;     }
.LBB0_1088:
	s_andn2_b64 vcc, exec, s[8:9]
	s_mov_b64 s[6:7], -1
	v_lshlrev_b32_e32 v183, 1, v156
	v_lshl_add_u32 v232, v152, 11, v183
	v_lshl_add_u32 v183, v152, 13, v183
	s_add_u32 s56, s20, 0x1800
	s_addc_u32 s57, s21, 0
	global_load_dwordx4 v[184:187], v183, s[56:57]
	global_load_dwordx4 v[188:191], v183, s[56:57] offset:256
	s_add_u32 s56, s20, 0x21800
	s_addc_u32 s57, s21, 0
	global_load_dwordx4 v[192:195], v183, s[56:57]
	global_load_dwordx4 v[196:199], v183, s[56:57] offset:256
	s_waitcnt vmcnt(3)
	v_lshlrev_b32_e32 v200, 16, v184
	v_and_b32_e32 v201, 0xffff0000, v184
	v_lshlrev_b32_e32 v202, 16, v185
	v_and_b32_e32 v203, 0xffff0000, v185
	v_lshlrev_b32_e32 v204, 16, v186
	v_and_b32_e32 v205, 0xffff0000, v186
	v_lshlrev_b32_e32 v206, 16, v187
	v_and_b32_e32 v207, 0xffff0000, v187
	s_add_u32 s56, s20, 0x41800
	s_addc_u32 s57, s21, 0
	global_load_dwordx4 v[184:187], v183, s[56:57]
	v_mul_f32_e32 v124, v124, v200
	v_mul_f32_e32 v125, v125, v201
	v_mul_f32_e32 v126, v126, v202
	v_mul_f32_e32 v127, v127, v203
	v_mul_f32_e32 v120, v120, v204
	v_mul_f32_e32 v121, v121, v205
	v_mul_f32_e32 v122, v122, v206
	v_mul_f32_e32 v123, v123, v207
	v_cvt_pk_bf16_f32 v124, v124, v125
	v_cvt_pk_bf16_f32 v125, v126, v127
	v_cvt_pk_bf16_f32 v126, v120, v121
	v_cvt_pk_bf16_f32 v127, v122, v123
	s_add_u32 s58, s70, 0x0
	s_addc_u32 s59, s71, 0
	global_store_dwordx4 v232, v[124:127], s[58:59]
	s_waitcnt vmcnt(4)
	v_lshlrev_b32_e32 v200, 16, v188
	v_and_b32_e32 v201, 0xffff0000, v188
	v_lshlrev_b32_e32 v202, 16, v189
	v_and_b32_e32 v203, 0xffff0000, v189
	v_lshlrev_b32_e32 v204, 16, v190
	v_and_b32_e32 v205, 0xffff0000, v190
	v_lshlrev_b32_e32 v206, 16, v191
	v_and_b32_e32 v207, 0xffff0000, v191
	global_load_dwordx4 v[188:191], v183, s[56:57] offset:256
	v_mul_f32_e32 v116, v116, v200
	v_mul_f32_e32 v117, v117, v201
	v_mul_f32_e32 v118, v118, v202
	v_mul_f32_e32 v119, v119, v203
	v_mul_f32_e32 v112, v112, v204
	v_mul_f32_e32 v113, v113, v205
	v_mul_f32_e32 v114, v114, v206
	v_mul_f32_e32 v115, v115, v207
	v_cvt_pk_bf16_f32 v116, v116, v117
	v_cvt_pk_bf16_f32 v117, v118, v119
	v_cvt_pk_bf16_f32 v118, v112, v113
	v_cvt_pk_bf16_f32 v119, v114, v115
	global_store_dwordx4 v232, v[116:119], s[58:59] offset:256
	s_waitcnt vmcnt(5)
	v_lshlrev_b32_e32 v200, 16, v192
	v_and_b32_e32 v201, 0xffff0000, v192
	v_lshlrev_b32_e32 v202, 16, v193
	v_and_b32_e32 v203, 0xffff0000, v193
	v_lshlrev_b32_e32 v204, 16, v194
	v_and_b32_e32 v205, 0xffff0000, v194
	v_lshlrev_b32_e32 v206, 16, v195
	v_and_b32_e32 v207, 0xffff0000, v195
	s_add_u32 s56, s20, 0x61800
	s_addc_u32 s57, s21, 0
	global_load_dwordx4 v[192:195], v183, s[56:57]
	v_mul_f32_e32 v108, v108, v200
	v_mul_f32_e32 v109, v109, v201
	v_mul_f32_e32 v110, v110, v202
	v_mul_f32_e32 v111, v111, v203
	v_mul_f32_e32 v104, v104, v204
	v_mul_f32_e32 v105, v105, v205
	v_mul_f32_e32 v106, v106, v206
	v_mul_f32_e32 v107, v107, v207
	v_cvt_pk_bf16_f32 v108, v108, v109
	v_cvt_pk_bf16_f32 v109, v110, v111
	v_cvt_pk_bf16_f32 v110, v104, v105
	v_cvt_pk_bf16_f32 v111, v106, v107
	s_add_u32 s58, s70, 0x8000
	s_addc_u32 s59, s71, 0
	global_store_dwordx4 v232, v[108:111], s[58:59]
	s_waitcnt vmcnt(6)
	v_lshlrev_b32_e32 v200, 16, v196
	v_and_b32_e32 v201, 0xffff0000, v196
	v_lshlrev_b32_e32 v202, 16, v197
	v_and_b32_e32 v203, 0xffff0000, v197
	v_lshlrev_b32_e32 v204, 16, v198
	v_and_b32_e32 v205, 0xffff0000, v198
	v_lshlrev_b32_e32 v206, 16, v199
	v_and_b32_e32 v207, 0xffff0000, v199
	global_load_dwordx4 v[196:199], v183, s[56:57] offset:256
	v_mul_f32_e32 v100, v100, v200
	v_mul_f32_e32 v101, v101, v201
	v_mul_f32_e32 v102, v102, v202
	v_mul_f32_e32 v103, v103, v203
	v_mul_f32_e32 v96, v96, v204
	v_mul_f32_e32 v97, v97, v205
	v_mul_f32_e32 v98, v98, v206
	v_mul_f32_e32 v99, v99, v207
	v_cvt_pk_bf16_f32 v100, v100, v101
	v_cvt_pk_bf16_f32 v101, v102, v103
	v_cvt_pk_bf16_f32 v102, v96, v97
	v_cvt_pk_bf16_f32 v103, v98, v99
	global_store_dwordx4 v232, v[100:103], s[58:59] offset:256
	s_waitcnt vmcnt(7)
	v_lshlrev_b32_e32 v200, 16, v184
	v_and_b32_e32 v201, 0xffff0000, v184
	v_lshlrev_b32_e32 v202, 16, v185
	v_and_b32_e32 v203, 0xffff0000, v185
	v_lshlrev_b32_e32 v204, 16, v186
	v_and_b32_e32 v205, 0xffff0000, v186
	v_lshlrev_b32_e32 v206, 16, v187
	v_and_b32_e32 v207, 0xffff0000, v187
	s_add_u32 s56, s20, 0x101800
	s_addc_u32 s57, s21, 0
	global_load_dwordx4 v[184:187], v183, s[56:57]
	v_mul_f32_e32 v92, v92, v200
	v_mul_f32_e32 v93, v93, v201
	v_mul_f32_e32 v94, v94, v202
	v_mul_f32_e32 v95, v95, v203
	v_mul_f32_e32 v88, v88, v204
	v_mul_f32_e32 v89, v89, v205
	v_mul_f32_e32 v90, v90, v206
	v_mul_f32_e32 v91, v91, v207
	v_cvt_pk_bf16_f32 v92, v92, v93
	v_cvt_pk_bf16_f32 v93, v94, v95
	v_cvt_pk_bf16_f32 v94, v88, v89
	v_cvt_pk_bf16_f32 v95, v90, v91
	s_add_u32 s58, s70, 0x10000
	s_addc_u32 s59, s71, 0
	global_store_dwordx4 v232, v[92:95], s[58:59]
	s_waitcnt vmcnt(7)
	v_lshlrev_b32_e32 v200, 16, v188
	v_and_b32_e32 v201, 0xffff0000, v188
	v_lshlrev_b32_e32 v202, 16, v189
	v_and_b32_e32 v203, 0xffff0000, v189
	v_lshlrev_b32_e32 v204, 16, v190
	v_and_b32_e32 v205, 0xffff0000, v190
	v_lshlrev_b32_e32 v206, 16, v191
	v_and_b32_e32 v207, 0xffff0000, v191
	global_load_dwordx4 v[188:191], v183, s[56:57] offset:256
	v_mul_f32_e32 v84, v84, v200
	v_mul_f32_e32 v85, v85, v201
	v_mul_f32_e32 v86, v86, v202
	v_mul_f32_e32 v87, v87, v203
	v_mul_f32_e32 v80, v80, v204
	v_mul_f32_e32 v81, v81, v205
	v_mul_f32_e32 v82, v82, v206
	v_mul_f32_e32 v83, v83, v207
	v_cvt_pk_bf16_f32 v84, v84, v85
	v_cvt_pk_bf16_f32 v85, v86, v87
	v_cvt_pk_bf16_f32 v86, v80, v81
	v_cvt_pk_bf16_f32 v87, v82, v83
	global_store_dwordx4 v232, v[84:87], s[58:59] offset:256
	s_waitcnt vmcnt(7)
; __device__ __forceinline__ unsigned cvt_pk_bf16(float lo, float hi) { f32x2_t v = {lo, hi}; bf16x2_t b = __builtin_convertvector(v, bf16x2_t); return __builtin_bit_cast(unsigned, b); }
; __device__ __forceinline__ float bf_lo(unsigned w) { return __uint_as_float(w << 16); }
; __device__ __forceinline__ float bf_hi(unsigned w) { return __uint_as_float(w & 0xffff0000u); }
;     __device__ __forceinline__ void operator()(const Acc& acc, const Unit& u, int wr, int wc, int fr, int fq) const {
;         const int row0 = u.pm * BM + wr * 64 + fr, col0 = u.pn * BM + wc * 32 + 8 * fq;
; #pragma unroll
;         for (int ai = 0; ai < 2; ++ai)
; #pragma unroll
;             for (int m = 0; m < 4; ++m) {
;                 const int row = row0 + ai * HALF + m * 16;
; #pragma unroll
;                 for (int bj = 0; bj < 2; ++bj) {
;                     const int col = col0 + bj * HALF;
;                     const u32x4 gb = *(const u32x4*)(P + (size_t)row * PP + C_GB + col);
;                     const float rb[8] = {bf_lo(gb.x), bf_hi(gb.x), bf_lo(gb.y), bf_hi(gb.y), bf_lo(gb.z), bf_hi(gb.z), bf_lo(gb.w), bf_hi(gb.w)};
;                     float o[8];
; #pragma unroll
;                     for (int n = 0; n < 2; ++n)
; #pragma unroll
;                         for (int e = 0; e < 4; ++e) o[4 * n + e] = acc[ai][bj][m][n][e] * rb[4 * n + e];
;                     u32x4 w; w.x = cvt_pk_bf16(o[0], o[1]); w.y = cvt_pk_bf16(o[2], o[3]); w.z = cvt_pk_bf16(o[4], o[5]); w.w = cvt_pk_bf16(o[6], o[7]);
;                     *(u32x4*)(OUT + (size_t)row * DM + col) = w;
;                 }
;             }
;     }
	v_lshlrev_b32_e32 v200, 16, v192
	v_and_b32_e32 v201, 0xffff0000, v192
	v_lshlrev_b32_e32 v202, 16, v193
	v_and_b32_e32 v203, 0xffff0000, v193
	v_lshlrev_b32_e32 v204, 16, v194
	v_and_b32_e32 v205, 0xffff0000, v194
	v_lshlrev_b32_e32 v206, 16, v195
	v_and_b32_e32 v207, 0xffff0000, v195
	s_add_u32 s56, s20, 0x121800
	s_addc_u32 s57, s21, 0
	global_load_dwordx4 v[192:195], v183, s[56:57]
	v_mul_f32_e32 v76, v76, v200
	v_mul_f32_e32 v77, v77, v201
	v_mul_f32_e32 v78, v78, v202
	v_mul_f32_e32 v79, v79, v203
	v_mul_f32_e32 v72, v72, v204
	v_mul_f32_e32 v73, v73, v205
	v_mul_f32_e32 v74, v74, v206
	v_mul_f32_e32 v75, v75, v207
	v_cvt_pk_bf16_f32 v76, v76, v77
	v_cvt_pk_bf16_f32 v77, v78, v79
	v_cvt_pk_bf16_f32 v78, v72, v73
	v_cvt_pk_bf16_f32 v79, v74, v75
	s_add_u32 s58, s70, 0x18000
	s_addc_u32 s59, s71, 0
	global_store_dwordx4 v232, v[76:79], s[58:59]
	s_waitcnt vmcnt(7)
	v_lshlrev_b32_e32 v200, 16, v196
	v_and_b32_e32 v201, 0xffff0000, v196
	v_lshlrev_b32_e32 v202, 16, v197
	v_and_b32_e32 v203, 0xffff0000, v197
	v_lshlrev_b32_e32 v204, 16, v198
	v_and_b32_e32 v205, 0xffff0000, v198
	v_lshlrev_b32_e32 v206, 16, v199
	v_and_b32_e32 v207, 0xffff0000, v199
	global_load_dwordx4 v[196:199], v183, s[56:57] offset:256
	v_mul_f32_e32 v68, v68, v200
	v_mul_f32_e32 v69, v69, v201
	v_mul_f32_e32 v70, v70, v202
	v_mul_f32_e32 v71, v71, v203
	v_mul_f32_e32 v64, v64, v204
	v_mul_f32_e32 v65, v65, v205
	v_mul_f32_e32 v66, v66, v206
	v_mul_f32_e32 v67, v67, v207
	v_cvt_pk_bf16_f32 v68, v68, v69
	v_cvt_pk_bf16_f32 v69, v70, v71
	v_cvt_pk_bf16_f32 v70, v64, v65
	v_cvt_pk_bf16_f32 v71, v66, v67
	global_store_dwordx4 v232, v[68:71], s[58:59] offset:256
	s_waitcnt vmcnt(7)
	v_lshlrev_b32_e32 v200, 16, v184
	v_and_b32_e32 v201, 0xffff0000, v184
	v_lshlrev_b32_e32 v202, 16, v185
	v_and_b32_e32 v203, 0xffff0000, v185
	v_lshlrev_b32_e32 v204, 16, v186
	v_and_b32_e32 v205, 0xffff0000, v186
	v_lshlrev_b32_e32 v206, 16, v187
	v_and_b32_e32 v207, 0xffff0000, v187
	s_add_u32 s56, s20, 0x141800
	s_addc_u32 s57, s21, 0
	global_load_dwordx4 v[184:187], v183, s[56:57]
	v_mul_f32_e32 v60, v60, v200
	v_mul_f32_e32 v61, v61, v201
	v_mul_f32_e32 v62, v62, v202
	v_mul_f32_e32 v63, v63, v203
	v_mul_f32_e32 v56, v56, v204
	v_mul_f32_e32 v57, v57, v205
	v_mul_f32_e32 v58, v58, v206
	v_mul_f32_e32 v59, v59, v207
	v_cvt_pk_bf16_f32 v60, v60, v61
	v_cvt_pk_bf16_f32 v61, v62, v63
	v_cvt_pk_bf16_f32 v62, v56, v57
	v_cvt_pk_bf16_f32 v63, v58, v59
	s_add_u32 s58, s70, 0x40000
	s_addc_u32 s59, s71, 0
	global_store_dwordx4 v232, v[60:63], s[58:59]
	s_waitcnt vmcnt(7)
	v_lshlrev_b32_e32 v200, 16, v188
	v_and_b32_e32 v201, 0xffff0000, v188
	v_lshlrev_b32_e32 v202, 16, v189
	v_and_b32_e32 v203, 0xffff0000, v189
	v_lshlrev_b32_e32 v204, 16, v190
	v_and_b32_e32 v205, 0xffff0000, v190
	v_lshlrev_b32_e32 v206, 16, v191
	v_and_b32_e32 v207, 0xffff0000, v191
	global_load_dwordx4 v[188:191], v183, s[56:57] offset:256
	v_mul_f32_e32 v52, v52, v200
	v_mul_f32_e32 v53, v53, v201
	v_mul_f32_e32 v54, v54, v202
	v_mul_f32_e32 v55, v55, v203
	v_mul_f32_e32 v48, v48, v204
	v_mul_f32_e32 v49, v49, v205
	v_mul_f32_e32 v50, v50, v206
	v_mul_f32_e32 v51, v51, v207
	v_cvt_pk_bf16_f32 v52, v52, v53
	v_cvt_pk_bf16_f32 v53, v54, v55
	v_cvt_pk_bf16_f32 v54, v48, v49
	v_cvt_pk_bf16_f32 v55, v50, v51
	global_store_dwordx4 v232, v[52:55], s[58:59] offset:256
	s_waitcnt vmcnt(7)
	v_lshlrev_b32_e32 v200, 16, v192
	v_and_b32_e32 v201, 0xffff0000, v192
	v_lshlrev_b32_e32 v202, 16, v193
	v_and_b32_e32 v203, 0xffff0000, v193
	v_lshlrev_b32_e32 v204, 16, v194
	v_and_b32_e32 v205, 0xffff0000, v194
	v_lshlrev_b32_e32 v206, 16, v195
	v_and_b32_e32 v207, 0xffff0000, v195
	s_add_u32 s56, s20, 0x161800
	s_addc_u32 s57, s21, 0
	global_load_dwordx4 v[192:195], v183, s[56:57]
	v_mul_f32_e32 v44, v44, v200
	v_mul_f32_e32 v45, v45, v201
	v_mul_f32_e32 v46, v46, v202
	v_mul_f32_e32 v47, v47, v203
	v_mul_f32_e32 v40, v40, v204
	v_mul_f32_e32 v41, v41, v205
	v_mul_f32_e32 v42, v42, v206
	v_mul_f32_e32 v43, v43, v207
	v_cvt_pk_bf16_f32 v44, v44, v45
	v_cvt_pk_bf16_f32 v45, v46, v47
	v_cvt_pk_bf16_f32 v46, v40, v41
	v_cvt_pk_bf16_f32 v47, v42, v43
	s_add_u32 s58, s70, 0x48000
	s_addc_u32 s59, s71, 0
	global_store_dwordx4 v232, v[44:47], s[58:59]
	s_waitcnt vmcnt(7)
; __device__ __forceinline__ unsigned cvt_pk_bf16(float lo, float hi) { f32x2_t v = {lo, hi}; bf16x2_t b = __builtin_convertvector(v, bf16x2_t); return __builtin_bit_cast(unsigned, b); }
; __device__ __forceinline__ float bf_lo(unsigned w) { return __uint_as_float(w << 16); }
; __device__ __forceinline__ float bf_hi(unsigned w) { return __uint_as_float(w & 0xffff0000u); }
; #define PG8_BAR __builtin_amdgcn_s_barrier()
; template <class Epi>
; __device__ __forceinline__ void gemm_phase(LAS unsigned char* lds, const Gemm g, const StaticOrder& S, const Epi& E) {
;     ...
;         if (!has_next) break;
; #pragma unroll
;         for (int a = 0; a < 2; ++a)
; #pragma unroll
;             for (int b = 0; b < 2; ++b)
; #pragma unroll
;                 for (int m = 0; m < 4; ++m)
; #pragma unroll
;                     for (int n = 0; n < 2; ++n) acc[a][b][m][n] = (f32x4){0.f, 0.f, 0.f, 0.f};
;         cur = nxt; cA = nA; cB = nB; ++ui;
;         if (wr == 1) PG8_BAR;
;     __device__ __forceinline__ void operator()(const Acc& acc, const Unit& u, int wr, int wc, int fr, int fq) const {
;         const int row0 = u.pm * BM + wr * 64 + fr, col0 = u.pn * BM + wc * 32 + 8 * fq;
; #pragma unroll
;         for (int ai = 0; ai < 2; ++ai)
; #pragma unroll
;             for (int m = 0; m < 4; ++m) {
;                 const int row = row0 + ai * HALF + m * 16;
; #pragma unroll
;                 for (int bj = 0; bj < 2; ++bj) {
;                     const int col = col0 + bj * HALF;
;                     const u32x4 gb = *(const u32x4*)(P + (size_t)row * PP + C_GB + col);
;                     const float rb[8] = {bf_lo(gb.x), bf_hi(gb.x), bf_lo(gb.y), bf_hi(gb.y), bf_lo(gb.z), bf_hi(gb.z), bf_lo(gb.w), bf_hi(gb.w)};
;                     float o[8];
; #pragma unroll
;                     for (int n = 0; n < 2; ++n)
; #pragma unroll
;                         for (int e = 0; e < 4; ++e) o[4 * n + e] = acc[ai][bj][m][n][e] * rb[4 * n + e];
;                     u32x4 w; w.x = cvt_pk_bf16(o[0], o[1]); w.y = cvt_pk_bf16(o[2], o[3]); w.z = cvt_pk_bf16(o[4], o[5]); w.w = cvt_pk_bf16(o[6], o[7]);
;                     *(u32x4*)(OUT + (size_t)row * DM + col) = w;
;                 }
;             }
;     }
	v_lshlrev_b32_e32 v200, 16, v196
	v_and_b32_e32 v201, 0xffff0000, v196
	v_lshlrev_b32_e32 v202, 16, v197
	v_and_b32_e32 v203, 0xffff0000, v197
	v_lshlrev_b32_e32 v204, 16, v198
	v_and_b32_e32 v205, 0xffff0000, v198
	v_lshlrev_b32_e32 v206, 16, v199
	v_and_b32_e32 v207, 0xffff0000, v199
	global_load_dwordx4 v[196:199], v183, s[56:57] offset:256
	v_mul_f32_e32 v36, v36, v200
	v_mul_f32_e32 v37, v37, v201
	v_mul_f32_e32 v38, v38, v202
	v_mul_f32_e32 v39, v39, v203
	v_mul_f32_e32 v32, v32, v204
	v_mul_f32_e32 v33, v33, v205
	v_mul_f32_e32 v34, v34, v206
	v_mul_f32_e32 v35, v35, v207
	v_cvt_pk_bf16_f32 v36, v36, v37
	v_cvt_pk_bf16_f32 v37, v38, v39
	v_cvt_pk_bf16_f32 v38, v32, v33
	v_cvt_pk_bf16_f32 v39, v34, v35
	global_store_dwordx4 v232, v[36:39], s[58:59] offset:256
	s_waitcnt vmcnt(7)
	v_lshlrev_b32_e32 v200, 16, v184
	v_and_b32_e32 v201, 0xffff0000, v184
	v_lshlrev_b32_e32 v202, 16, v185
	v_and_b32_e32 v203, 0xffff0000, v185
	v_lshlrev_b32_e32 v204, 16, v186
	v_and_b32_e32 v205, 0xffff0000, v186
	v_lshlrev_b32_e32 v206, 16, v187
	v_and_b32_e32 v207, 0xffff0000, v187
	v_mul_f32_e32 v28, v28, v200
	v_mul_f32_e32 v29, v29, v201
	v_mul_f32_e32 v30, v30, v202
	v_mul_f32_e32 v31, v31, v203
	v_mul_f32_e32 v24, v24, v204
	v_mul_f32_e32 v25, v25, v205
	v_mul_f32_e32 v26, v26, v206
	v_mul_f32_e32 v27, v27, v207
	v_cvt_pk_bf16_f32 v28, v28, v29
	v_cvt_pk_bf16_f32 v29, v30, v31
	v_cvt_pk_bf16_f32 v30, v24, v25
	v_cvt_pk_bf16_f32 v31, v26, v27
	s_add_u32 s58, s70, 0x50000
	s_addc_u32 s59, s71, 0
	global_store_dwordx4 v232, v[28:31], s[58:59]
	s_waitcnt vmcnt(6)
	v_lshlrev_b32_e32 v200, 16, v188
	v_and_b32_e32 v201, 0xffff0000, v188
	v_lshlrev_b32_e32 v202, 16, v189
	v_and_b32_e32 v203, 0xffff0000, v189
	v_lshlrev_b32_e32 v204, 16, v190
	v_and_b32_e32 v205, 0xffff0000, v190
	v_lshlrev_b32_e32 v206, 16, v191
	v_and_b32_e32 v207, 0xffff0000, v191
	v_mul_f32_e32 v20, v20, v200
	v_mul_f32_e32 v21, v21, v201
	v_mul_f32_e32 v22, v22, v202
	v_mul_f32_e32 v23, v23, v203
	v_mul_f32_e32 v16, v16, v204
	v_mul_f32_e32 v17, v17, v205
	v_mul_f32_e32 v18, v18, v206
	v_mul_f32_e32 v19, v19, v207
	v_cvt_pk_bf16_f32 v20, v20, v21
	v_cvt_pk_bf16_f32 v21, v22, v23
	v_cvt_pk_bf16_f32 v22, v16, v17
	v_cvt_pk_bf16_f32 v23, v18, v19
	global_store_dwordx4 v232, v[20:23], s[58:59] offset:256
	s_waitcnt vmcnt(5)
	v_lshlrev_b32_e32 v200, 16, v192
	v_and_b32_e32 v201, 0xffff0000, v192
	v_lshlrev_b32_e32 v202, 16, v193
	v_and_b32_e32 v203, 0xffff0000, v193
	v_lshlrev_b32_e32 v204, 16, v194
	v_and_b32_e32 v205, 0xffff0000, v194
	v_lshlrev_b32_e32 v206, 16, v195
	v_and_b32_e32 v207, 0xffff0000, v195
	v_mul_f32_e32 v12, v12, v200
	v_mul_f32_e32 v13, v13, v201
	v_mul_f32_e32 v14, v14, v202
	v_mul_f32_e32 v15, v15, v203
	v_mul_f32_e32 v8, v8, v204
	v_mul_f32_e32 v9, v9, v205
	v_mul_f32_e32 v10, v10, v206
	v_mul_f32_e32 v11, v11, v207
	v_cvt_pk_bf16_f32 v12, v12, v13
	v_cvt_pk_bf16_f32 v13, v14, v15
	v_cvt_pk_bf16_f32 v14, v8, v9
	v_cvt_pk_bf16_f32 v15, v10, v11
	s_add_u32 s58, s70, 0x58000
	s_addc_u32 s59, s71, 0
	global_store_dwordx4 v232, v[12:15], s[58:59]
	s_waitcnt vmcnt(4)
	v_lshlrev_b32_e32 v200, 16, v196
	v_and_b32_e32 v201, 0xffff0000, v196
	v_lshlrev_b32_e32 v202, 16, v197
	v_and_b32_e32 v203, 0xffff0000, v197
	v_lshlrev_b32_e32 v204, 16, v198
	v_and_b32_e32 v205, 0xffff0000, v198
	v_lshlrev_b32_e32 v206, 16, v199
	v_and_b32_e32 v207, 0xffff0000, v199
	v_mul_f32_e32 v4, v4, v200
	v_mul_f32_e32 v5, v5, v201
	v_mul_f32_e32 v6, v6, v202
	v_mul_f32_e32 v7, v7, v203
	v_mul_f32_e32 v0, v0, v204
	v_mul_f32_e32 v1, v1, v205
	v_mul_f32_e32 v2, v2, v206
	v_mul_f32_e32 v3, v3, v207
	v_cvt_pk_bf16_f32 v4, v4, v5
	v_cvt_pk_bf16_f32 v5, v6, v7
	v_cvt_pk_bf16_f32 v6, v0, v1
	v_cvt_pk_bf16_f32 v7, v2, v3
	global_store_dwordx4 v232, v[4:7], s[58:59] offset:256
	s_cbranch_vccnz .LBB0_1075
	s_andn2_b64 vcc, exec, s[2:3]
	s_cbranch_vccnz .LBB0_1074
	s_barrier
	s_branch .LBB0_1074
